# plus FFN-up conv+SiLU epilogue as a per-thread sliding window over 16 consecutive rows (less LDS re-read/unpack/bookkeeping)
# speedup vs baseline: 1.0796x; 1.0122x over previous
.LBB0_640:
	s_and_b64 s[2:3], s[8:9], exec
	s_waitcnt vmcnt(0)
	v_readlane_b32 s2, v255, 15
	v_readlane_b32 s4, v255, 19
	v_readlane_b32 s3, v255, 16
	v_readlane_b32 s5, v255, 20
	s_cselect_b32 s42, s2, s4
	v_readlane_b32 s2, v255, 17
	s_cselect_b32 s28, s51, 0
	s_cselect_b32 s29, s52, 0
	s_cselect_b32 s43, s3, s5
	s_cselect_b32 s46, s2, 0
	s_cmp_lt_i32 s44, 4
	s_mov_b64 s[2:3], -1
	s_waitcnt vmcnt(0) lgkmcnt(0)
	s_barrier
	s_cbranch_scc1 .LBB0_1047
	s_cmp_lt_i32 s44, 6
	s_cbranch_scc1 .LBB0_1041
	s_cmp_gt_i32 s44, 6
	s_cbranch_scc0 .LBB0_654
	s_movk_i32 s15, 0x210
	v_lshlrev_b32_e32 v0, 3, v223
	v_mul_lo_u32 v132, v225, s15
	v_cvt_pk_bf16_f32 v131, v128, v129
	v_cvt_pk_bf16_f32 v130, v126, v127
	v_add3_u32 v0, v224, v132, v0
	v_cvt_pk_bf16_f32 v133, v124, v125
	v_cvt_pk_bf16_f32 v132, v122, v123
	ds_write2_b64 v0, v[130:131], v[132:133] offset1:4
	v_cvt_pk_bf16_f32 v131, v120, v121
	v_cvt_pk_bf16_f32 v130, v118, v119
	v_cvt_pk_bf16_f32 v133, v116, v117
	v_cvt_pk_bf16_f32 v132, v114, v115
	ds_write2_b64 v0, v[130:131], v[132:133] offset0:32 offset1:36
	v_cvt_pk_bf16_f32 v131, v112, v113
	v_cvt_pk_bf16_f32 v130, v110, v111
	v_cvt_pk_bf16_f32 v133, v108, v109
	v_cvt_pk_bf16_f32 v132, v106, v107
	v_add_u32_e32 v134, 0x2000, v0
	ds_write2_b64 v134, v[130:131], v[132:133] offset0:32 offset1:36
	v_cvt_pk_bf16_f32 v131, v104, v105
	v_cvt_pk_bf16_f32 v130, v102, v103
	v_cvt_pk_bf16_f32 v133, v100, v101
	v_cvt_pk_bf16_f32 v132, v98, v99
	ds_write2_b64 v134, v[130:131], v[132:133] offset0:64 offset1:68
	v_cvt_pk_bf16_f32 v131, v96, v97
	v_cvt_pk_bf16_f32 v130, v94, v95
	v_cvt_pk_bf16_f32 v133, v92, v93
	v_cvt_pk_bf16_f32 v132, v90, v91
	v_add_u32_e32 v134, 0x4000, v0
	ds_write2_b64 v134, v[130:131], v[132:133] offset0:64 offset1:68
	v_cvt_pk_bf16_f32 v131, v88, v89
	v_cvt_pk_bf16_f32 v130, v86, v87
	v_cvt_pk_bf16_f32 v133, v84, v85
	v_cvt_pk_bf16_f32 v132, v82, v83
	ds_write2_b64 v134, v[130:131], v[132:133] offset0:96 offset1:100
	v_cvt_pk_bf16_f32 v131, v80, v81
	v_cvt_pk_bf16_f32 v130, v78, v79
	v_cvt_pk_bf16_f32 v133, v76, v77
	v_cvt_pk_bf16_f32 v132, v74, v75
	v_add_u32_e32 v134, 0x6000, v0
	ds_write2_b64 v134, v[130:131], v[132:133] offset0:96 offset1:100
	v_cvt_pk_bf16_f32 v131, v72, v73
	v_cvt_pk_bf16_f32 v130, v70, v71
	v_cvt_pk_bf16_f32 v133, v68, v69
	v_cvt_pk_bf16_f32 v132, v66, v67
	ds_write2_b64 v134, v[130:131], v[132:133] offset0:128 offset1:132
	v_cvt_pk_bf16_f32 v131, v64, v65
	v_cvt_pk_bf16_f32 v130, v62, v63
	v_cvt_pk_bf16_f32 v133, v60, v61
	v_cvt_pk_bf16_f32 v132, v58, v59
	v_add_u32_e32 v134, 0x8000, v0
	ds_write2_b64 v134, v[130:131], v[132:133] offset0:128 offset1:132
	v_cvt_pk_bf16_f32 v131, v56, v57
	v_cvt_pk_bf16_f32 v130, v54, v55
	v_cvt_pk_bf16_f32 v133, v52, v53
	v_cvt_pk_bf16_f32 v132, v50, v51
	ds_write2_b64 v134, v[130:131], v[132:133] offset0:160 offset1:164
	v_cvt_pk_bf16_f32 v131, v48, v49
	v_cvt_pk_bf16_f32 v130, v46, v47
	v_cvt_pk_bf16_f32 v133, v44, v45
	v_cvt_pk_bf16_f32 v132, v42, v43
	v_add_u32_e32 v134, 0xa000, v0
	ds_write2_b64 v134, v[130:131], v[132:133] offset0:160 offset1:164
	v_cvt_pk_bf16_f32 v131, v36, v37
	v_cvt_pk_bf16_f32 v130, v34, v35
	v_cvt_pk_bf16_f32 v133, v32, v33
	v_cvt_pk_bf16_f32 v132, v30, v31
	ds_write2_b64 v134, v[130:131], v[132:133] offset0:192 offset1:196
	v_cvt_pk_bf16_f32 v131, v40, v41
	v_cvt_pk_bf16_f32 v130, v38, v39
	v_cvt_pk_bf16_f32 v133, v28, v29
	v_cvt_pk_bf16_f32 v132, v26, v27
	v_add_u32_e32 v134, 0xc000, v0
	ds_write2_b64 v134, v[130:131], v[132:133] offset0:192 offset1:196
	v_cvt_pk_bf16_f32 v131, v24, v25
	v_cvt_pk_bf16_f32 v130, v22, v23
	v_cvt_pk_bf16_f32 v133, v20, v21
	v_cvt_pk_bf16_f32 v132, v18, v19
	ds_write2_b64 v134, v[130:131], v[132:133] offset0:224 offset1:228
	v_cvt_pk_bf16_f32 v131, v16, v17
	v_cvt_pk_bf16_f32 v130, v14, v15
	v_cvt_pk_bf16_f32 v133, v12, v13
	v_cvt_pk_bf16_f32 v132, v10, v11
	v_add_u32_e32 v134, 0xe000, v0
	ds_write2_b64 v134, v[130:131], v[132:133] offset0:224 offset1:228
	v_cvt_pk_bf16_f32 v131, v8, v9
	v_cvt_pk_bf16_f32 v130, v6, v7
	v_cvt_pk_bf16_f32 v133, v4, v5
	v_cvt_pk_bf16_f32 v132, v2, v3
	v_add_u32_e32 v0, 0xe800, v0
	ds_write2_b64 v0, v[130:131], v[132:133] offset1:4
	v_lshlrev_b32_e32 v0, 2, v175
	v_and_b32_e32 v0, 0x7c, v0
	s_mul_i32 s2, s28, 0x10800
	v_readlane_b32 s48, v253, 61
	v_lshl_or_b32 v164, s47, 7, v0
	s_mul_hi_u32 s3, s28, 0x10800
	v_readlane_b32 s49, v253, 62
	s_add_u32 s2, s48, s2
	v_ashrrev_i32_e32 v165, 31, v164
	s_addc_u32 s3, s49, s3
	v_lshlrev_b64 v[130:131], 2, v[164:165]
	v_lshl_add_u64 v[150:151], s[2:3], 0, v[130:131]
	s_movk_i32 s2, 0x5000
	v_add_co_u32_e32 v134, vcc, s2, v150
	s_mov_b32 s2, 0xb000
	s_nop 0
	v_addc_co_u32_e32 v135, vcc, 0, v151, vcc
	v_add_co_u32_e32 v138, vcc, s2, v150
	v_readlane_b32 s50, v253, 63
	s_nop 0
	v_addc_co_u32_e32 v139, vcc, 0, v151, vcc
	v_add_co_u32_e32 v142, vcc, s25, v150
	s_mul_i32 s4, s28, 0x5800
	s_nop 0
	v_addc_co_u32_e32 v143, vcc, 0, v151, vcc
	s_mov_b32 s2, 0x8000
	v_readlane_b32 s51, v254, 0
	s_mul_hi_u32 s5, s28, 0x5800
	s_add_u32 s4, s50, s4
	v_add_co_u32_e32 v146, vcc, s2, v150
	s_addc_u32 s5, s51, s5
	s_nop 0
	v_addc_co_u32_e32 v147, vcc, 0, v151, vcc
	s_mov_b32 s2, 0xd000
	s_waitcnt lgkmcnt(0)
	s_barrier
	v_lshl_add_u64 v[158:159], s[4:5], 0, v[130:131]
	global_load_dwordx4 v[130:133], v[150:151], off
	v_add_co_u32_e32 v150, vcc, s2, v150
	global_load_dwordx4 v[134:137], v[134:135], off offset:2048
	s_nop 0
	global_load_dwordx4 v[138:141], v[138:139], off
	v_addc_co_u32_e32 v151, vcc, 0, v151, vcc
	global_load_dwordx4 v[142:145], v[142:143], off offset:3072
	s_nop 0
	global_load_dwordx4 v[146:149], v[146:147], off offset:1024
	s_nop 0
	global_load_dwordx4 v[150:153], v[150:151], off offset:3072
	s_nop 0
	global_load_dwordx4 v[154:157], v[158:159], off
	v_add_co_u32_e32 v158, vcc, 0x2000, v158
	v_ashrrev_i32_e32 v0, 5, v175
	s_nop 0
	v_addc_co_u32_e32 v159, vcc, 0, v159, vcc
	global_load_dwordx4 v[158:161], v[158:159], off offset:3072
	v_readlane_b32 s2, v252, 32
	v_readlane_b32 s3, v252, 33
	v_mul_lo_u32 v166, v0, s15
	v_and_b32_e32 v167, 31, v175
	s_mov_b32 s14, 0
	v_lshl_add_u64 v[164:165], v[164:165], 1, s[2:3]
	v_lshl_add_u32 v166, v167, 3, v166
	v_add_u32_e32 v167, s40, v0
	s_waitcnt vmcnt(0)
	s_mov_b32 s14, 0x8800
	v_mul_u32_u24_e32 v63, 0x2100, v0
	v_and_b32_e32 v64, 31, v175
	v_lshl_add_u32 v63, v64, 3, v63
	v_lshlrev_b32_e32 v61, 4, v0
	v_add_u32_e32 v61, 1, v61
	v_add_u32_e32 v62, s40, v61
	s_mov_b32 s4, 0x78787879
	v_mul_hi_i32 v60, v62, s4
	v_lshrrev_b32_e32 v64, 31, v60
	v_ashrrev_i32_e32 v60, 11, v60
	v_add_u32_e32 v60, v60, v64
	v_mul_i32_i24_e32 v60, 0x1100, v60
	v_sub_u32_e32 v60, v62, v60
	s_movk_i32 s4, 0x1600
	v_mad_i64_i32 v[58:59], s[4:5], v62, s4, v[164:165]
	v_mov_b32_e32 v56, 0x1600
	v_mov_b32_e32 v57, 0
	ds_read2_b64 v[26:29], v63 offset1:32
	ds_read2_b64 v[68:71], v63 offset0:66 offset1:98
	s_waitcnt lgkmcnt(0)
	v_lshlrev_b32_e32 v2, 16, v26
	v_and_b32_e32 v3, 0xffff0000, v26
	v_lshlrev_b32_e32 v4, 16, v27
	v_and_b32_e32 v5, 0xffff0000, v27
	v_lshlrev_b32_e32 v14, 16, v28
	v_and_b32_e32 v15, 0xffff0000, v28
	v_lshlrev_b32_e32 v16, 16, v29
	v_and_b32_e32 v17, 0xffff0000, v29
	v_lshlrev_b32_e32 v6, 16, v68
	v_and_b32_e32 v7, 0xffff0000, v68
	v_lshlrev_b32_e32 v8, 16, v69
	v_and_b32_e32 v9, 0xffff0000, v69
	v_lshlrev_b32_e32 v18, 16, v70
	v_and_b32_e32 v19, 0xffff0000, v70
	v_lshlrev_b32_e32 v20, 16, v71
	v_and_b32_e32 v21, 0xffff0000, v71
	v_add_u32_e32 v63, 0x420, v63
	ds_read2_b64 v[26:29], v63 offset1:32
	v_and_b32_e32 v64, 0xfffffeff, v60
	v_and_b32_e32 v65, 0xffffefff, v60
	v_cmp_eq_u32_e32 vcc, 0, v64
	v_cmp_eq_u32_e64 s[2:3], s33, v65
	v_add_u32_e32 v63, 0x210, v63
	s_nop 0
	v_cndmask_b32_e64 v52, 1.0, 0, vcc
	v_cndmask_b32_e64 v54, 1.0, 0, s[2:3]
	s_waitcnt lgkmcnt(0)
	v_lshlrev_b32_e32 v10, 16, v26
	v_and_b32_e32 v11, 0xffff0000, v26
	v_lshlrev_b32_e32 v12, 16, v27
	v_and_b32_e32 v13, 0xffff0000, v27
	v_lshlrev_b32_e32 v22, 16, v28
	v_and_b32_e32 v23, 0xffff0000, v28
	v_lshlrev_b32_e32 v24, 16, v29
	v_and_b32_e32 v25, 0xffff0000, v29
	v_pk_fma_f32 v[30:31], v[146:147], v[18:19], v[158:159]
	v_pk_fma_f32 v[32:33], v[148:149], v[20:21], v[160:161]
	v_pk_mul_f32 v[38:39], v[52:53], v[14:15] op_sel_hi:[0,1]
	v_pk_mul_f32 v[40:41], v[52:53], v[16:17] op_sel_hi:[0,1]
	v_pk_fma_f32 v[30:31], v[142:143], v[38:39], v[30:31]
	v_pk_fma_f32 v[32:33], v[144:145], v[40:41], v[32:33]
	v_pk_mul_f32 v[38:39], v[54:55], v[22:23] op_sel_hi:[0,1]
	v_pk_mul_f32 v[40:41], v[54:55], v[24:25] op_sel_hi:[0,1]
	v_pk_fma_f32 v[30:31], v[150:151], v[38:39], v[30:31]
	v_pk_fma_f32 v[32:33], v[152:153], v[40:41], v[32:33]
	v_pk_fma_f32 v[34:35], v[134:135], v[6:7], v[154:155]
	v_pk_fma_f32 v[36:37], v[136:137], v[8:9], v[156:157]
	v_pk_mul_f32 v[38:39], v[52:53], v[2:3] op_sel_hi:[0,1]
	v_pk_mul_f32 v[40:41], v[52:53], v[4:5] op_sel_hi:[0,1]
	v_pk_fma_f32 v[34:35], v[130:131], v[38:39], v[34:35]
	v_pk_fma_f32 v[36:37], v[132:133], v[40:41], v[36:37]
	v_pk_mul_f32 v[38:39], v[54:55], v[10:11] op_sel_hi:[0,1]
	v_pk_mul_f32 v[40:41], v[54:55], v[12:13] op_sel_hi:[0,1]
	v_pk_fma_f32 v[34:35], v[138:139], v[38:39], v[34:35]
	v_pk_fma_f32 v[36:37], v[140:141], v[40:41], v[36:37]
	v_mul_f32_e32 v42, 0xbfb8aa3b, v30
	v_exp_f32_e32 v42, v42
	v_mul_f32_e32 v43, 0xbfb8aa3b, v31
	v_exp_f32_e32 v43, v43
	v_mul_f32_e32 v44, 0xbfb8aa3b, v32
	v_exp_f32_e32 v44, v44
	v_mul_f32_e32 v45, 0xbfb8aa3b, v33
	v_exp_f32_e32 v45, v45
	v_pk_add_f32 v[42:43], v[42:43], 1.0 op_sel_hi:[1,0]
	v_pk_add_f32 v[44:45], v[44:45], 1.0 op_sel_hi:[1,0]
	v_rcp_f32_e32 v46, v42
	v_rcp_f32_e32 v47, v43
	v_rcp_f32_e32 v48, v44
	v_rcp_f32_e32 v49, v45
	v_mul_f32_e32 v46, v30, v46
	v_mul_f32_e32 v47, v31, v47
	v_mul_f32_e32 v48, v32, v48
	v_mul_f32_e32 v49, v33, v49
	v_pk_mul_f32 v[34:35], v[34:35], v[46:47]
	v_pk_mul_f32 v[36:37], v[36:37], v[48:49]
	v_cvt_pk_bf16_f32 v66, v34, v35
	v_cvt_pk_bf16_f32 v67, v36, v37
	v_cmp_gt_i32_e32 vcc, s33, v61
	v_cmp_gt_i32_e64 s[2:3], s14, v62
	v_add_u32_e32 v61, 1, v61
	v_add_u32_e32 v62, 1, v62
	s_and_b64 s[2:3], vcc, s[2:3]
	s_and_saveexec_b64 s[4:5], s[2:3]
	global_store_dwordx2 v[58:59], v[66:67], off
	s_or_b64 exec, exec, s[4:5]
	v_add_u32_e32 v60, 1, v60
	v_lshl_add_u64 v[58:59], v[58:59], 0, v[56:57]
	v_cmp_ne_u32_e32 vcc, 0x1100, v60
	s_nop 1
	v_cndmask_b32_e32 v60, 0, v60, vcc
	ds_read2_b64 v[26:29], v63 offset1:32
	v_and_b32_e32 v64, 0xfffffeff, v60
	v_and_b32_e32 v65, 0xffffefff, v60
	v_cmp_eq_u32_e32 vcc, 0, v64
	v_cmp_eq_u32_e64 s[2:3], s33, v65
	v_add_u32_e32 v63, 0x210, v63
	s_nop 0
	v_cndmask_b32_e64 v52, 1.0, 0, vcc
	v_cndmask_b32_e64 v54, 1.0, 0, s[2:3]
	s_waitcnt lgkmcnt(0)
	v_lshlrev_b32_e32 v2, 16, v26
	v_and_b32_e32 v3, 0xffff0000, v26
	v_lshlrev_b32_e32 v4, 16, v27
	v_and_b32_e32 v5, 0xffff0000, v27
	v_lshlrev_b32_e32 v14, 16, v28
	v_and_b32_e32 v15, 0xffff0000, v28
	v_lshlrev_b32_e32 v16, 16, v29
	v_and_b32_e32 v17, 0xffff0000, v29
	v_pk_fma_f32 v[30:31], v[146:147], v[22:23], v[158:159]
	v_pk_fma_f32 v[32:33], v[148:149], v[24:25], v[160:161]
	v_pk_mul_f32 v[38:39], v[52:53], v[18:19] op_sel_hi:[0,1]
	v_pk_mul_f32 v[40:41], v[52:53], v[20:21] op_sel_hi:[0,1]
	v_pk_fma_f32 v[30:31], v[142:143], v[38:39], v[30:31]
	v_pk_fma_f32 v[32:33], v[144:145], v[40:41], v[32:33]
	v_pk_mul_f32 v[38:39], v[54:55], v[14:15] op_sel_hi:[0,1]
	v_pk_mul_f32 v[40:41], v[54:55], v[16:17] op_sel_hi:[0,1]
	v_pk_fma_f32 v[30:31], v[150:151], v[38:39], v[30:31]
	v_pk_fma_f32 v[32:33], v[152:153], v[40:41], v[32:33]
	v_pk_fma_f32 v[34:35], v[134:135], v[10:11], v[154:155]
	v_pk_fma_f32 v[36:37], v[136:137], v[12:13], v[156:157]
	v_pk_mul_f32 v[38:39], v[52:53], v[6:7] op_sel_hi:[0,1]
	v_pk_mul_f32 v[40:41], v[52:53], v[8:9] op_sel_hi:[0,1]
	v_pk_fma_f32 v[34:35], v[130:131], v[38:39], v[34:35]
	v_pk_fma_f32 v[36:37], v[132:133], v[40:41], v[36:37]
	v_pk_mul_f32 v[38:39], v[54:55], v[2:3] op_sel_hi:[0,1]
	v_pk_mul_f32 v[40:41], v[54:55], v[4:5] op_sel_hi:[0,1]
	v_pk_fma_f32 v[34:35], v[138:139], v[38:39], v[34:35]
	v_pk_fma_f32 v[36:37], v[140:141], v[40:41], v[36:37]
	v_mul_f32_e32 v42, 0xbfb8aa3b, v30
	v_exp_f32_e32 v42, v42
	v_mul_f32_e32 v43, 0xbfb8aa3b, v31
	v_exp_f32_e32 v43, v43
	v_mul_f32_e32 v44, 0xbfb8aa3b, v32
	v_exp_f32_e32 v44, v44
	v_mul_f32_e32 v45, 0xbfb8aa3b, v33
	v_exp_f32_e32 v45, v45
	v_pk_add_f32 v[42:43], v[42:43], 1.0 op_sel_hi:[1,0]
	v_pk_add_f32 v[44:45], v[44:45], 1.0 op_sel_hi:[1,0]
	v_rcp_f32_e32 v46, v42
	v_rcp_f32_e32 v47, v43
	v_rcp_f32_e32 v48, v44
	v_rcp_f32_e32 v49, v45
	v_mul_f32_e32 v46, v30, v46
	v_mul_f32_e32 v47, v31, v47
	v_mul_f32_e32 v48, v32, v48
	v_mul_f32_e32 v49, v33, v49
	v_pk_mul_f32 v[34:35], v[34:35], v[46:47]
	v_pk_mul_f32 v[36:37], v[36:37], v[48:49]
	v_cvt_pk_bf16_f32 v66, v34, v35
	v_cvt_pk_bf16_f32 v67, v36, v37
	v_cmp_gt_i32_e32 vcc, s33, v61
	v_cmp_gt_i32_e64 s[2:3], s14, v62
	v_add_u32_e32 v61, 1, v61
	v_add_u32_e32 v62, 1, v62
	s_and_b64 s[2:3], vcc, s[2:3]
	s_and_saveexec_b64 s[4:5], s[2:3]
	global_store_dwordx2 v[58:59], v[66:67], off
	s_or_b64 exec, exec, s[4:5]
	v_add_u32_e32 v60, 1, v60
	v_lshl_add_u64 v[58:59], v[58:59], 0, v[56:57]
	v_cmp_ne_u32_e32 vcc, 0x1100, v60
	s_nop 1
	v_cndmask_b32_e32 v60, 0, v60, vcc
	ds_read2_b64 v[26:29], v63 offset1:32
	v_and_b32_e32 v64, 0xfffffeff, v60
	v_and_b32_e32 v65, 0xffffefff, v60
	v_cmp_eq_u32_e32 vcc, 0, v64
	v_cmp_eq_u32_e64 s[2:3], s33, v65
	v_add_u32_e32 v63, 0x210, v63
	s_nop 0
	v_cndmask_b32_e64 v52, 1.0, 0, vcc
	v_cndmask_b32_e64 v54, 1.0, 0, s[2:3]
	s_waitcnt lgkmcnt(0)
	v_lshlrev_b32_e32 v6, 16, v26
	v_and_b32_e32 v7, 0xffff0000, v26
	v_lshlrev_b32_e32 v8, 16, v27
	v_and_b32_e32 v9, 0xffff0000, v27
	v_lshlrev_b32_e32 v18, 16, v28
	v_and_b32_e32 v19, 0xffff0000, v28
	v_lshlrev_b32_e32 v20, 16, v29
	v_and_b32_e32 v21, 0xffff0000, v29
	v_pk_fma_f32 v[30:31], v[146:147], v[14:15], v[158:159]
	v_pk_fma_f32 v[32:33], v[148:149], v[16:17], v[160:161]
	v_pk_mul_f32 v[38:39], v[52:53], v[22:23] op_sel_hi:[0,1]
	v_pk_mul_f32 v[40:41], v[52:53], v[24:25] op_sel_hi:[0,1]
	v_pk_fma_f32 v[30:31], v[142:143], v[38:39], v[30:31]
	v_pk_fma_f32 v[32:33], v[144:145], v[40:41], v[32:33]
	v_pk_mul_f32 v[38:39], v[54:55], v[18:19] op_sel_hi:[0,1]
	v_pk_mul_f32 v[40:41], v[54:55], v[20:21] op_sel_hi:[0,1]
	v_pk_fma_f32 v[30:31], v[150:151], v[38:39], v[30:31]
	v_pk_fma_f32 v[32:33], v[152:153], v[40:41], v[32:33]
	v_pk_fma_f32 v[34:35], v[134:135], v[2:3], v[154:155]
	v_pk_fma_f32 v[36:37], v[136:137], v[4:5], v[156:157]
	v_pk_mul_f32 v[38:39], v[52:53], v[10:11] op_sel_hi:[0,1]
	v_pk_mul_f32 v[40:41], v[52:53], v[12:13] op_sel_hi:[0,1]
	v_pk_fma_f32 v[34:35], v[130:131], v[38:39], v[34:35]
	v_pk_fma_f32 v[36:37], v[132:133], v[40:41], v[36:37]
	v_pk_mul_f32 v[38:39], v[54:55], v[6:7] op_sel_hi:[0,1]
	v_pk_mul_f32 v[40:41], v[54:55], v[8:9] op_sel_hi:[0,1]
	v_pk_fma_f32 v[34:35], v[138:139], v[38:39], v[34:35]
	v_pk_fma_f32 v[36:37], v[140:141], v[40:41], v[36:37]
	v_mul_f32_e32 v42, 0xbfb8aa3b, v30
	v_exp_f32_e32 v42, v42
	v_mul_f32_e32 v43, 0xbfb8aa3b, v31
	v_exp_f32_e32 v43, v43
	v_mul_f32_e32 v44, 0xbfb8aa3b, v32
	v_exp_f32_e32 v44, v44
	v_mul_f32_e32 v45, 0xbfb8aa3b, v33
	v_exp_f32_e32 v45, v45
	v_pk_add_f32 v[42:43], v[42:43], 1.0 op_sel_hi:[1,0]
	v_pk_add_f32 v[44:45], v[44:45], 1.0 op_sel_hi:[1,0]
	v_rcp_f32_e32 v46, v42
	v_rcp_f32_e32 v47, v43
	v_rcp_f32_e32 v48, v44
	v_rcp_f32_e32 v49, v45
	v_mul_f32_e32 v46, v30, v46
	v_mul_f32_e32 v47, v31, v47
	v_mul_f32_e32 v48, v32, v48
	v_mul_f32_e32 v49, v33, v49
	v_pk_mul_f32 v[34:35], v[34:35], v[46:47]
	v_pk_mul_f32 v[36:37], v[36:37], v[48:49]
	v_cvt_pk_bf16_f32 v66, v34, v35
	v_cvt_pk_bf16_f32 v67, v36, v37
	v_cmp_gt_i32_e32 vcc, s33, v61
	v_cmp_gt_i32_e64 s[2:3], s14, v62
	v_add_u32_e32 v61, 1, v61
	v_add_u32_e32 v62, 1, v62
	s_and_b64 s[2:3], vcc, s[2:3]
	s_and_saveexec_b64 s[4:5], s[2:3]
	global_store_dwordx2 v[58:59], v[66:67], off
	s_or_b64 exec, exec, s[4:5]
	v_add_u32_e32 v60, 1, v60
	v_lshl_add_u64 v[58:59], v[58:59], 0, v[56:57]
	v_cmp_ne_u32_e32 vcc, 0x1100, v60
	s_nop 1
	v_cndmask_b32_e32 v60, 0, v60, vcc
	ds_read2_b64 v[26:29], v63 offset1:32
	v_and_b32_e32 v64, 0xfffffeff, v60
	v_and_b32_e32 v65, 0xffffefff, v60
	v_cmp_eq_u32_e32 vcc, 0, v64
	v_cmp_eq_u32_e64 s[2:3], s33, v65
	v_add_u32_e32 v63, 0x210, v63
	s_nop 0
	v_cndmask_b32_e64 v52, 1.0, 0, vcc
	v_cndmask_b32_e64 v54, 1.0, 0, s[2:3]
	s_waitcnt lgkmcnt(0)
	v_lshlrev_b32_e32 v10, 16, v26
	v_and_b32_e32 v11, 0xffff0000, v26
	v_lshlrev_b32_e32 v12, 16, v27
	v_and_b32_e32 v13, 0xffff0000, v27
	v_lshlrev_b32_e32 v22, 16, v28
	v_and_b32_e32 v23, 0xffff0000, v28
	v_lshlrev_b32_e32 v24, 16, v29
	v_and_b32_e32 v25, 0xffff0000, v29
	v_pk_fma_f32 v[30:31], v[146:147], v[18:19], v[158:159]
	v_pk_fma_f32 v[32:33], v[148:149], v[20:21], v[160:161]
	v_pk_mul_f32 v[38:39], v[52:53], v[14:15] op_sel_hi:[0,1]
	v_pk_mul_f32 v[40:41], v[52:53], v[16:17] op_sel_hi:[0,1]
	v_pk_fma_f32 v[30:31], v[142:143], v[38:39], v[30:31]
	v_pk_fma_f32 v[32:33], v[144:145], v[40:41], v[32:33]
	v_pk_mul_f32 v[38:39], v[54:55], v[22:23] op_sel_hi:[0,1]
	v_pk_mul_f32 v[40:41], v[54:55], v[24:25] op_sel_hi:[0,1]
	v_pk_fma_f32 v[30:31], v[150:151], v[38:39], v[30:31]
	v_pk_fma_f32 v[32:33], v[152:153], v[40:41], v[32:33]
	v_pk_fma_f32 v[34:35], v[134:135], v[6:7], v[154:155]
	v_pk_fma_f32 v[36:37], v[136:137], v[8:9], v[156:157]
	v_pk_mul_f32 v[38:39], v[52:53], v[2:3] op_sel_hi:[0,1]
	v_pk_mul_f32 v[40:41], v[52:53], v[4:5] op_sel_hi:[0,1]
	v_pk_fma_f32 v[34:35], v[130:131], v[38:39], v[34:35]
	v_pk_fma_f32 v[36:37], v[132:133], v[40:41], v[36:37]
	v_pk_mul_f32 v[38:39], v[54:55], v[10:11] op_sel_hi:[0,1]
	v_pk_mul_f32 v[40:41], v[54:55], v[12:13] op_sel_hi:[0,1]
	v_pk_fma_f32 v[34:35], v[138:139], v[38:39], v[34:35]
	v_pk_fma_f32 v[36:37], v[140:141], v[40:41], v[36:37]
	v_mul_f32_e32 v42, 0xbfb8aa3b, v30
	v_exp_f32_e32 v42, v42
	v_mul_f32_e32 v43, 0xbfb8aa3b, v31
	v_exp_f32_e32 v43, v43
	v_mul_f32_e32 v44, 0xbfb8aa3b, v32
	v_exp_f32_e32 v44, v44
	v_mul_f32_e32 v45, 0xbfb8aa3b, v33
	v_exp_f32_e32 v45, v45
	v_pk_add_f32 v[42:43], v[42:43], 1.0 op_sel_hi:[1,0]
	v_pk_add_f32 v[44:45], v[44:45], 1.0 op_sel_hi:[1,0]
	v_rcp_f32_e32 v46, v42
	v_rcp_f32_e32 v47, v43
	v_rcp_f32_e32 v48, v44
	v_rcp_f32_e32 v49, v45
	v_mul_f32_e32 v46, v30, v46
	v_mul_f32_e32 v47, v31, v47
	v_mul_f32_e32 v48, v32, v48
	v_mul_f32_e32 v49, v33, v49
	v_pk_mul_f32 v[34:35], v[34:35], v[46:47]
	v_pk_mul_f32 v[36:37], v[36:37], v[48:49]
	v_cvt_pk_bf16_f32 v66, v34, v35
	v_cvt_pk_bf16_f32 v67, v36, v37
	v_cmp_gt_i32_e32 vcc, s33, v61
	v_cmp_gt_i32_e64 s[2:3], s14, v62
	v_add_u32_e32 v61, 1, v61
	v_add_u32_e32 v62, 1, v62
	s_and_b64 s[2:3], vcc, s[2:3]
	s_and_saveexec_b64 s[4:5], s[2:3]
	global_store_dwordx2 v[58:59], v[66:67], off
	s_or_b64 exec, exec, s[4:5]
	v_add_u32_e32 v60, 1, v60
	v_lshl_add_u64 v[58:59], v[58:59], 0, v[56:57]
	v_cmp_ne_u32_e32 vcc, 0x1100, v60
	s_nop 1
	v_cndmask_b32_e32 v60, 0, v60, vcc
	ds_read2_b64 v[26:29], v63 offset1:32
	v_and_b32_e32 v64, 0xfffffeff, v60
	v_and_b32_e32 v65, 0xffffefff, v60
	v_cmp_eq_u32_e32 vcc, 0, v64
	v_cmp_eq_u32_e64 s[2:3], s33, v65
	v_add_u32_e32 v63, 0x210, v63
	s_nop 0
	v_cndmask_b32_e64 v52, 1.0, 0, vcc
	v_cndmask_b32_e64 v54, 1.0, 0, s[2:3]
	s_waitcnt lgkmcnt(0)
	v_lshlrev_b32_e32 v2, 16, v26
	v_and_b32_e32 v3, 0xffff0000, v26
	v_lshlrev_b32_e32 v4, 16, v27
	v_and_b32_e32 v5, 0xffff0000, v27
	v_lshlrev_b32_e32 v14, 16, v28
	v_and_b32_e32 v15, 0xffff0000, v28
	v_lshlrev_b32_e32 v16, 16, v29
	v_and_b32_e32 v17, 0xffff0000, v29
	v_pk_fma_f32 v[30:31], v[146:147], v[22:23], v[158:159]
	v_pk_fma_f32 v[32:33], v[148:149], v[24:25], v[160:161]
	v_pk_mul_f32 v[38:39], v[52:53], v[18:19] op_sel_hi:[0,1]
	v_pk_mul_f32 v[40:41], v[52:53], v[20:21] op_sel_hi:[0,1]
	v_pk_fma_f32 v[30:31], v[142:143], v[38:39], v[30:31]
	v_pk_fma_f32 v[32:33], v[144:145], v[40:41], v[32:33]
	v_pk_mul_f32 v[38:39], v[54:55], v[14:15] op_sel_hi:[0,1]
	v_pk_mul_f32 v[40:41], v[54:55], v[16:17] op_sel_hi:[0,1]
	v_pk_fma_f32 v[30:31], v[150:151], v[38:39], v[30:31]
	v_pk_fma_f32 v[32:33], v[152:153], v[40:41], v[32:33]
	v_pk_fma_f32 v[34:35], v[134:135], v[10:11], v[154:155]
	v_pk_fma_f32 v[36:37], v[136:137], v[12:13], v[156:157]
	v_pk_mul_f32 v[38:39], v[52:53], v[6:7] op_sel_hi:[0,1]
	v_pk_mul_f32 v[40:41], v[52:53], v[8:9] op_sel_hi:[0,1]
	v_pk_fma_f32 v[34:35], v[130:131], v[38:39], v[34:35]
	v_pk_fma_f32 v[36:37], v[132:133], v[40:41], v[36:37]
	v_pk_mul_f32 v[38:39], v[54:55], v[2:3] op_sel_hi:[0,1]
	v_pk_mul_f32 v[40:41], v[54:55], v[4:5] op_sel_hi:[0,1]
	v_pk_fma_f32 v[34:35], v[138:139], v[38:39], v[34:35]
	v_pk_fma_f32 v[36:37], v[140:141], v[40:41], v[36:37]
	v_mul_f32_e32 v42, 0xbfb8aa3b, v30
	v_exp_f32_e32 v42, v42
	v_mul_f32_e32 v43, 0xbfb8aa3b, v31
	v_exp_f32_e32 v43, v43
	v_mul_f32_e32 v44, 0xbfb8aa3b, v32
	v_exp_f32_e32 v44, v44
	v_mul_f32_e32 v45, 0xbfb8aa3b, v33
	v_exp_f32_e32 v45, v45
	v_pk_add_f32 v[42:43], v[42:43], 1.0 op_sel_hi:[1,0]
	v_pk_add_f32 v[44:45], v[44:45], 1.0 op_sel_hi:[1,0]
	v_rcp_f32_e32 v46, v42
	v_rcp_f32_e32 v47, v43
	v_rcp_f32_e32 v48, v44
	v_rcp_f32_e32 v49, v45
	v_mul_f32_e32 v46, v30, v46
	v_mul_f32_e32 v47, v31, v47
	v_mul_f32_e32 v48, v32, v48
	v_mul_f32_e32 v49, v33, v49
	v_pk_mul_f32 v[34:35], v[34:35], v[46:47]
	v_pk_mul_f32 v[36:37], v[36:37], v[48:49]
	v_cvt_pk_bf16_f32 v66, v34, v35
	v_cvt_pk_bf16_f32 v67, v36, v37
	v_cmp_gt_i32_e32 vcc, s33, v61
	v_cmp_gt_i32_e64 s[2:3], s14, v62
	v_add_u32_e32 v61, 1, v61
	v_add_u32_e32 v62, 1, v62
	s_and_b64 s[2:3], vcc, s[2:3]
	s_and_saveexec_b64 s[4:5], s[2:3]
	global_store_dwordx2 v[58:59], v[66:67], off
	s_or_b64 exec, exec, s[4:5]
	v_add_u32_e32 v60, 1, v60
	v_lshl_add_u64 v[58:59], v[58:59], 0, v[56:57]
	v_cmp_ne_u32_e32 vcc, 0x1100, v60
	s_nop 1
	v_cndmask_b32_e32 v60, 0, v60, vcc
	ds_read2_b64 v[26:29], v63 offset1:32
	v_and_b32_e32 v64, 0xfffffeff, v60
	v_and_b32_e32 v65, 0xffffefff, v60
	v_cmp_eq_u32_e32 vcc, 0, v64
	v_cmp_eq_u32_e64 s[2:3], s33, v65
	v_add_u32_e32 v63, 0x210, v63
	s_nop 0
	v_cndmask_b32_e64 v52, 1.0, 0, vcc
	v_cndmask_b32_e64 v54, 1.0, 0, s[2:3]
	s_waitcnt lgkmcnt(0)
	v_lshlrev_b32_e32 v6, 16, v26
	v_and_b32_e32 v7, 0xffff0000, v26
	v_lshlrev_b32_e32 v8, 16, v27
	v_and_b32_e32 v9, 0xffff0000, v27
	v_lshlrev_b32_e32 v18, 16, v28
	v_and_b32_e32 v19, 0xffff0000, v28
	v_lshlrev_b32_e32 v20, 16, v29
	v_and_b32_e32 v21, 0xffff0000, v29
	v_pk_fma_f32 v[30:31], v[146:147], v[14:15], v[158:159]
	v_pk_fma_f32 v[32:33], v[148:149], v[16:17], v[160:161]
	v_pk_mul_f32 v[38:39], v[52:53], v[22:23] op_sel_hi:[0,1]
	v_pk_mul_f32 v[40:41], v[52:53], v[24:25] op_sel_hi:[0,1]
	v_pk_fma_f32 v[30:31], v[142:143], v[38:39], v[30:31]
	v_pk_fma_f32 v[32:33], v[144:145], v[40:41], v[32:33]
	v_pk_mul_f32 v[38:39], v[54:55], v[18:19] op_sel_hi:[0,1]
	v_pk_mul_f32 v[40:41], v[54:55], v[20:21] op_sel_hi:[0,1]
	v_pk_fma_f32 v[30:31], v[150:151], v[38:39], v[30:31]
	v_pk_fma_f32 v[32:33], v[152:153], v[40:41], v[32:33]
	v_pk_fma_f32 v[34:35], v[134:135], v[2:3], v[154:155]
	v_pk_fma_f32 v[36:37], v[136:137], v[4:5], v[156:157]
	v_pk_mul_f32 v[38:39], v[52:53], v[10:11] op_sel_hi:[0,1]
	v_pk_mul_f32 v[40:41], v[52:53], v[12:13] op_sel_hi:[0,1]
	v_pk_fma_f32 v[34:35], v[130:131], v[38:39], v[34:35]
	v_pk_fma_f32 v[36:37], v[132:133], v[40:41], v[36:37]
	v_pk_mul_f32 v[38:39], v[54:55], v[6:7] op_sel_hi:[0,1]
	v_pk_mul_f32 v[40:41], v[54:55], v[8:9] op_sel_hi:[0,1]
	v_pk_fma_f32 v[34:35], v[138:139], v[38:39], v[34:35]
	v_pk_fma_f32 v[36:37], v[140:141], v[40:41], v[36:37]
	v_mul_f32_e32 v42, 0xbfb8aa3b, v30
	v_exp_f32_e32 v42, v42
	v_mul_f32_e32 v43, 0xbfb8aa3b, v31
	v_exp_f32_e32 v43, v43
	v_mul_f32_e32 v44, 0xbfb8aa3b, v32
	v_exp_f32_e32 v44, v44
	v_mul_f32_e32 v45, 0xbfb8aa3b, v33
	v_exp_f32_e32 v45, v45
	v_pk_add_f32 v[42:43], v[42:43], 1.0 op_sel_hi:[1,0]
	v_pk_add_f32 v[44:45], v[44:45], 1.0 op_sel_hi:[1,0]
	v_rcp_f32_e32 v46, v42
	v_rcp_f32_e32 v47, v43
	v_rcp_f32_e32 v48, v44
	v_rcp_f32_e32 v49, v45
	v_mul_f32_e32 v46, v30, v46
	v_mul_f32_e32 v47, v31, v47
	v_mul_f32_e32 v48, v32, v48
	v_mul_f32_e32 v49, v33, v49
	v_pk_mul_f32 v[34:35], v[34:35], v[46:47]
	v_pk_mul_f32 v[36:37], v[36:37], v[48:49]
	v_cvt_pk_bf16_f32 v66, v34, v35
	v_cvt_pk_bf16_f32 v67, v36, v37
	v_cmp_gt_i32_e32 vcc, s33, v61
	v_cmp_gt_i32_e64 s[2:3], s14, v62
	v_add_u32_e32 v61, 1, v61
	v_add_u32_e32 v62, 1, v62
	s_and_b64 s[2:3], vcc, s[2:3]
	s_and_saveexec_b64 s[4:5], s[2:3]
	global_store_dwordx2 v[58:59], v[66:67], off
	s_or_b64 exec, exec, s[4:5]
	v_add_u32_e32 v60, 1, v60
	v_lshl_add_u64 v[58:59], v[58:59], 0, v[56:57]
	v_cmp_ne_u32_e32 vcc, 0x1100, v60
	s_nop 1
	v_cndmask_b32_e32 v60, 0, v60, vcc
	ds_read2_b64 v[26:29], v63 offset1:32
	v_and_b32_e32 v64, 0xfffffeff, v60
	v_and_b32_e32 v65, 0xffffefff, v60
	v_cmp_eq_u32_e32 vcc, 0, v64
	v_cmp_eq_u32_e64 s[2:3], s33, v65
	v_add_u32_e32 v63, 0x210, v63
	s_nop 0
	v_cndmask_b32_e64 v52, 1.0, 0, vcc
	v_cndmask_b32_e64 v54, 1.0, 0, s[2:3]
	s_waitcnt lgkmcnt(0)
	v_lshlrev_b32_e32 v10, 16, v26
	v_and_b32_e32 v11, 0xffff0000, v26
	v_lshlrev_b32_e32 v12, 16, v27
	v_and_b32_e32 v13, 0xffff0000, v27
	v_lshlrev_b32_e32 v22, 16, v28
	v_and_b32_e32 v23, 0xffff0000, v28
	v_lshlrev_b32_e32 v24, 16, v29
	v_and_b32_e32 v25, 0xffff0000, v29
	v_pk_fma_f32 v[30:31], v[146:147], v[18:19], v[158:159]
	v_pk_fma_f32 v[32:33], v[148:149], v[20:21], v[160:161]
	v_pk_mul_f32 v[38:39], v[52:53], v[14:15] op_sel_hi:[0,1]
	v_pk_mul_f32 v[40:41], v[52:53], v[16:17] op_sel_hi:[0,1]
	v_pk_fma_f32 v[30:31], v[142:143], v[38:39], v[30:31]
	v_pk_fma_f32 v[32:33], v[144:145], v[40:41], v[32:33]
	v_pk_mul_f32 v[38:39], v[54:55], v[22:23] op_sel_hi:[0,1]
	v_pk_mul_f32 v[40:41], v[54:55], v[24:25] op_sel_hi:[0,1]
	v_pk_fma_f32 v[30:31], v[150:151], v[38:39], v[30:31]
	v_pk_fma_f32 v[32:33], v[152:153], v[40:41], v[32:33]
	v_pk_fma_f32 v[34:35], v[134:135], v[6:7], v[154:155]
	v_pk_fma_f32 v[36:37], v[136:137], v[8:9], v[156:157]
	v_pk_mul_f32 v[38:39], v[52:53], v[2:3] op_sel_hi:[0,1]
	v_pk_mul_f32 v[40:41], v[52:53], v[4:5] op_sel_hi:[0,1]
	v_pk_fma_f32 v[34:35], v[130:131], v[38:39], v[34:35]
	v_pk_fma_f32 v[36:37], v[132:133], v[40:41], v[36:37]
	v_pk_mul_f32 v[38:39], v[54:55], v[10:11] op_sel_hi:[0,1]
	v_pk_mul_f32 v[40:41], v[54:55], v[12:13] op_sel_hi:[0,1]
	v_pk_fma_f32 v[34:35], v[138:139], v[38:39], v[34:35]
	v_pk_fma_f32 v[36:37], v[140:141], v[40:41], v[36:37]
	v_mul_f32_e32 v42, 0xbfb8aa3b, v30
	v_exp_f32_e32 v42, v42
	v_mul_f32_e32 v43, 0xbfb8aa3b, v31
	v_exp_f32_e32 v43, v43
	v_mul_f32_e32 v44, 0xbfb8aa3b, v32
	v_exp_f32_e32 v44, v44
	v_mul_f32_e32 v45, 0xbfb8aa3b, v33
	v_exp_f32_e32 v45, v45
	v_pk_add_f32 v[42:43], v[42:43], 1.0 op_sel_hi:[1,0]
	v_pk_add_f32 v[44:45], v[44:45], 1.0 op_sel_hi:[1,0]
	v_rcp_f32_e32 v46, v42
	v_rcp_f32_e32 v47, v43
	v_rcp_f32_e32 v48, v44
	v_rcp_f32_e32 v49, v45
	v_mul_f32_e32 v46, v30, v46
	v_mul_f32_e32 v47, v31, v47
	v_mul_f32_e32 v48, v32, v48
	v_mul_f32_e32 v49, v33, v49
	v_pk_mul_f32 v[34:35], v[34:35], v[46:47]
	v_pk_mul_f32 v[36:37], v[36:37], v[48:49]
	v_cvt_pk_bf16_f32 v66, v34, v35
	v_cvt_pk_bf16_f32 v67, v36, v37
	v_cmp_gt_i32_e32 vcc, s33, v61
	v_cmp_gt_i32_e64 s[2:3], s14, v62
	v_add_u32_e32 v61, 1, v61
	v_add_u32_e32 v62, 1, v62
	s_and_b64 s[2:3], vcc, s[2:3]
	s_and_saveexec_b64 s[4:5], s[2:3]
	global_store_dwordx2 v[58:59], v[66:67], off
	s_or_b64 exec, exec, s[4:5]
	v_add_u32_e32 v60, 1, v60
	v_lshl_add_u64 v[58:59], v[58:59], 0, v[56:57]
	v_cmp_ne_u32_e32 vcc, 0x1100, v60
	s_nop 1
	v_cndmask_b32_e32 v60, 0, v60, vcc
	ds_read2_b64 v[26:29], v63 offset1:32
	v_and_b32_e32 v64, 0xfffffeff, v60
	v_and_b32_e32 v65, 0xffffefff, v60
	v_cmp_eq_u32_e32 vcc, 0, v64
	v_cmp_eq_u32_e64 s[2:3], s33, v65
	v_add_u32_e32 v63, 0x210, v63
	s_nop 0
	v_cndmask_b32_e64 v52, 1.0, 0, vcc
	v_cndmask_b32_e64 v54, 1.0, 0, s[2:3]
	s_waitcnt lgkmcnt(0)
	v_lshlrev_b32_e32 v2, 16, v26
	v_and_b32_e32 v3, 0xffff0000, v26
	v_lshlrev_b32_e32 v4, 16, v27
	v_and_b32_e32 v5, 0xffff0000, v27
	v_lshlrev_b32_e32 v14, 16, v28
	v_and_b32_e32 v15, 0xffff0000, v28
	v_lshlrev_b32_e32 v16, 16, v29
	v_and_b32_e32 v17, 0xffff0000, v29
	v_pk_fma_f32 v[30:31], v[146:147], v[22:23], v[158:159]
	v_pk_fma_f32 v[32:33], v[148:149], v[24:25], v[160:161]
	v_pk_mul_f32 v[38:39], v[52:53], v[18:19] op_sel_hi:[0,1]
	v_pk_mul_f32 v[40:41], v[52:53], v[20:21] op_sel_hi:[0,1]
	v_pk_fma_f32 v[30:31], v[142:143], v[38:39], v[30:31]
	v_pk_fma_f32 v[32:33], v[144:145], v[40:41], v[32:33]
	v_pk_mul_f32 v[38:39], v[54:55], v[14:15] op_sel_hi:[0,1]
	v_pk_mul_f32 v[40:41], v[54:55], v[16:17] op_sel_hi:[0,1]
	v_pk_fma_f32 v[30:31], v[150:151], v[38:39], v[30:31]
	v_pk_fma_f32 v[32:33], v[152:153], v[40:41], v[32:33]
	v_pk_fma_f32 v[34:35], v[134:135], v[10:11], v[154:155]
	v_pk_fma_f32 v[36:37], v[136:137], v[12:13], v[156:157]
	v_pk_mul_f32 v[38:39], v[52:53], v[6:7] op_sel_hi:[0,1]
	v_pk_mul_f32 v[40:41], v[52:53], v[8:9] op_sel_hi:[0,1]
	v_pk_fma_f32 v[34:35], v[130:131], v[38:39], v[34:35]
	v_pk_fma_f32 v[36:37], v[132:133], v[40:41], v[36:37]
	v_pk_mul_f32 v[38:39], v[54:55], v[2:3] op_sel_hi:[0,1]
	v_pk_mul_f32 v[40:41], v[54:55], v[4:5] op_sel_hi:[0,1]
	v_pk_fma_f32 v[34:35], v[138:139], v[38:39], v[34:35]
	v_pk_fma_f32 v[36:37], v[140:141], v[40:41], v[36:37]
	v_mul_f32_e32 v42, 0xbfb8aa3b, v30
	v_exp_f32_e32 v42, v42
	v_mul_f32_e32 v43, 0xbfb8aa3b, v31
	v_exp_f32_e32 v43, v43
	v_mul_f32_e32 v44, 0xbfb8aa3b, v32
	v_exp_f32_e32 v44, v44
	v_mul_f32_e32 v45, 0xbfb8aa3b, v33
	v_exp_f32_e32 v45, v45
	v_pk_add_f32 v[42:43], v[42:43], 1.0 op_sel_hi:[1,0]
	v_pk_add_f32 v[44:45], v[44:45], 1.0 op_sel_hi:[1,0]
	v_rcp_f32_e32 v46, v42
	v_rcp_f32_e32 v47, v43
	v_rcp_f32_e32 v48, v44
	v_rcp_f32_e32 v49, v45
	v_mul_f32_e32 v46, v30, v46
	v_mul_f32_e32 v47, v31, v47
	v_mul_f32_e32 v48, v32, v48
	v_mul_f32_e32 v49, v33, v49
	v_pk_mul_f32 v[34:35], v[34:35], v[46:47]
	v_pk_mul_f32 v[36:37], v[36:37], v[48:49]
	v_cvt_pk_bf16_f32 v66, v34, v35
	v_cvt_pk_bf16_f32 v67, v36, v37
	v_cmp_gt_i32_e32 vcc, s33, v61
	v_cmp_gt_i32_e64 s[2:3], s14, v62
	v_add_u32_e32 v61, 1, v61
	v_add_u32_e32 v62, 1, v62
	s_and_b64 s[2:3], vcc, s[2:3]
	s_and_saveexec_b64 s[4:5], s[2:3]
	global_store_dwordx2 v[58:59], v[66:67], off
	s_or_b64 exec, exec, s[4:5]
	v_add_u32_e32 v60, 1, v60
	v_lshl_add_u64 v[58:59], v[58:59], 0, v[56:57]
	v_cmp_ne_u32_e32 vcc, 0x1100, v60
	s_nop 1
	v_cndmask_b32_e32 v60, 0, v60, vcc
	ds_read2_b64 v[26:29], v63 offset1:32
	v_and_b32_e32 v64, 0xfffffeff, v60
	v_and_b32_e32 v65, 0xffffefff, v60
	v_cmp_eq_u32_e32 vcc, 0, v64
	v_cmp_eq_u32_e64 s[2:3], s33, v65
	v_add_u32_e32 v63, 0x210, v63
	s_nop 0
	v_cndmask_b32_e64 v52, 1.0, 0, vcc
	v_cndmask_b32_e64 v54, 1.0, 0, s[2:3]
	s_waitcnt lgkmcnt(0)
	v_lshlrev_b32_e32 v6, 16, v26
	v_and_b32_e32 v7, 0xffff0000, v26
	v_lshlrev_b32_e32 v8, 16, v27
	v_and_b32_e32 v9, 0xffff0000, v27
	v_lshlrev_b32_e32 v18, 16, v28
	v_and_b32_e32 v19, 0xffff0000, v28
	v_lshlrev_b32_e32 v20, 16, v29
	v_and_b32_e32 v21, 0xffff0000, v29
	v_pk_fma_f32 v[30:31], v[146:147], v[14:15], v[158:159]
	v_pk_fma_f32 v[32:33], v[148:149], v[16:17], v[160:161]
	v_pk_mul_f32 v[38:39], v[52:53], v[22:23] op_sel_hi:[0,1]
	v_pk_mul_f32 v[40:41], v[52:53], v[24:25] op_sel_hi:[0,1]
	v_pk_fma_f32 v[30:31], v[142:143], v[38:39], v[30:31]
	v_pk_fma_f32 v[32:33], v[144:145], v[40:41], v[32:33]
	v_pk_mul_f32 v[38:39], v[54:55], v[18:19] op_sel_hi:[0,1]
	v_pk_mul_f32 v[40:41], v[54:55], v[20:21] op_sel_hi:[0,1]
	v_pk_fma_f32 v[30:31], v[150:151], v[38:39], v[30:31]
	v_pk_fma_f32 v[32:33], v[152:153], v[40:41], v[32:33]
	v_pk_fma_f32 v[34:35], v[134:135], v[2:3], v[154:155]
	v_pk_fma_f32 v[36:37], v[136:137], v[4:5], v[156:157]
	v_pk_mul_f32 v[38:39], v[52:53], v[10:11] op_sel_hi:[0,1]
	v_pk_mul_f32 v[40:41], v[52:53], v[12:13] op_sel_hi:[0,1]
	v_pk_fma_f32 v[34:35], v[130:131], v[38:39], v[34:35]
	v_pk_fma_f32 v[36:37], v[132:133], v[40:41], v[36:37]
	v_pk_mul_f32 v[38:39], v[54:55], v[6:7] op_sel_hi:[0,1]
	v_pk_mul_f32 v[40:41], v[54:55], v[8:9] op_sel_hi:[0,1]
	v_pk_fma_f32 v[34:35], v[138:139], v[38:39], v[34:35]
	v_pk_fma_f32 v[36:37], v[140:141], v[40:41], v[36:37]
	v_mul_f32_e32 v42, 0xbfb8aa3b, v30
	v_exp_f32_e32 v42, v42
	v_mul_f32_e32 v43, 0xbfb8aa3b, v31
	v_exp_f32_e32 v43, v43
	v_mul_f32_e32 v44, 0xbfb8aa3b, v32
	v_exp_f32_e32 v44, v44
	v_mul_f32_e32 v45, 0xbfb8aa3b, v33
	v_exp_f32_e32 v45, v45
	v_pk_add_f32 v[42:43], v[42:43], 1.0 op_sel_hi:[1,0]
	v_pk_add_f32 v[44:45], v[44:45], 1.0 op_sel_hi:[1,0]
	v_rcp_f32_e32 v46, v42
	v_rcp_f32_e32 v47, v43
	v_rcp_f32_e32 v48, v44
	v_rcp_f32_e32 v49, v45
	v_mul_f32_e32 v46, v30, v46
	v_mul_f32_e32 v47, v31, v47
	v_mul_f32_e32 v48, v32, v48
	v_mul_f32_e32 v49, v33, v49
	v_pk_mul_f32 v[34:35], v[34:35], v[46:47]
	v_pk_mul_f32 v[36:37], v[36:37], v[48:49]
	v_cvt_pk_bf16_f32 v66, v34, v35
	v_cvt_pk_bf16_f32 v67, v36, v37
	v_cmp_gt_i32_e32 vcc, s33, v61
	v_cmp_gt_i32_e64 s[2:3], s14, v62
	v_add_u32_e32 v61, 1, v61
	v_add_u32_e32 v62, 1, v62
	s_and_b64 s[2:3], vcc, s[2:3]
	s_and_saveexec_b64 s[4:5], s[2:3]
	global_store_dwordx2 v[58:59], v[66:67], off
	s_or_b64 exec, exec, s[4:5]
	v_add_u32_e32 v60, 1, v60
	v_lshl_add_u64 v[58:59], v[58:59], 0, v[56:57]
	v_cmp_ne_u32_e32 vcc, 0x1100, v60
	s_nop 1
	v_cndmask_b32_e32 v60, 0, v60, vcc
	ds_read2_b64 v[26:29], v63 offset1:32
	v_and_b32_e32 v64, 0xfffffeff, v60
	v_and_b32_e32 v65, 0xffffefff, v60
	v_cmp_eq_u32_e32 vcc, 0, v64
	v_cmp_eq_u32_e64 s[2:3], s33, v65
	v_add_u32_e32 v63, 0x210, v63
	s_nop 0
	v_cndmask_b32_e64 v52, 1.0, 0, vcc
	v_cndmask_b32_e64 v54, 1.0, 0, s[2:3]
	s_waitcnt lgkmcnt(0)
	v_lshlrev_b32_e32 v10, 16, v26
	v_and_b32_e32 v11, 0xffff0000, v26
	v_lshlrev_b32_e32 v12, 16, v27
	v_and_b32_e32 v13, 0xffff0000, v27
	v_lshlrev_b32_e32 v22, 16, v28
	v_and_b32_e32 v23, 0xffff0000, v28
	v_lshlrev_b32_e32 v24, 16, v29
	v_and_b32_e32 v25, 0xffff0000, v29
	v_pk_fma_f32 v[30:31], v[146:147], v[18:19], v[158:159]
	v_pk_fma_f32 v[32:33], v[148:149], v[20:21], v[160:161]
	v_pk_mul_f32 v[38:39], v[52:53], v[14:15] op_sel_hi:[0,1]
	v_pk_mul_f32 v[40:41], v[52:53], v[16:17] op_sel_hi:[0,1]
	v_pk_fma_f32 v[30:31], v[142:143], v[38:39], v[30:31]
	v_pk_fma_f32 v[32:33], v[144:145], v[40:41], v[32:33]
	v_pk_mul_f32 v[38:39], v[54:55], v[22:23] op_sel_hi:[0,1]
	v_pk_mul_f32 v[40:41], v[54:55], v[24:25] op_sel_hi:[0,1]
	v_pk_fma_f32 v[30:31], v[150:151], v[38:39], v[30:31]
	v_pk_fma_f32 v[32:33], v[152:153], v[40:41], v[32:33]
	v_pk_fma_f32 v[34:35], v[134:135], v[6:7], v[154:155]
	v_pk_fma_f32 v[36:37], v[136:137], v[8:9], v[156:157]
	v_pk_mul_f32 v[38:39], v[52:53], v[2:3] op_sel_hi:[0,1]
	v_pk_mul_f32 v[40:41], v[52:53], v[4:5] op_sel_hi:[0,1]
	v_pk_fma_f32 v[34:35], v[130:131], v[38:39], v[34:35]
	v_pk_fma_f32 v[36:37], v[132:133], v[40:41], v[36:37]
	v_pk_mul_f32 v[38:39], v[54:55], v[10:11] op_sel_hi:[0,1]
	v_pk_mul_f32 v[40:41], v[54:55], v[12:13] op_sel_hi:[0,1]
	v_pk_fma_f32 v[34:35], v[138:139], v[38:39], v[34:35]
	v_pk_fma_f32 v[36:37], v[140:141], v[40:41], v[36:37]
	v_mul_f32_e32 v42, 0xbfb8aa3b, v30
	v_exp_f32_e32 v42, v42
	v_mul_f32_e32 v43, 0xbfb8aa3b, v31
	v_exp_f32_e32 v43, v43
	v_mul_f32_e32 v44, 0xbfb8aa3b, v32
	v_exp_f32_e32 v44, v44
	v_mul_f32_e32 v45, 0xbfb8aa3b, v33
	v_exp_f32_e32 v45, v45
	v_pk_add_f32 v[42:43], v[42:43], 1.0 op_sel_hi:[1,0]
	v_pk_add_f32 v[44:45], v[44:45], 1.0 op_sel_hi:[1,0]
	v_rcp_f32_e32 v46, v42
	v_rcp_f32_e32 v47, v43
	v_rcp_f32_e32 v48, v44
	v_rcp_f32_e32 v49, v45
	v_mul_f32_e32 v46, v30, v46
	v_mul_f32_e32 v47, v31, v47
	v_mul_f32_e32 v48, v32, v48
	v_mul_f32_e32 v49, v33, v49
	v_pk_mul_f32 v[34:35], v[34:35], v[46:47]
	v_pk_mul_f32 v[36:37], v[36:37], v[48:49]
	v_cvt_pk_bf16_f32 v66, v34, v35
	v_cvt_pk_bf16_f32 v67, v36, v37
	v_cmp_gt_i32_e32 vcc, s33, v61
	v_cmp_gt_i32_e64 s[2:3], s14, v62
	v_add_u32_e32 v61, 1, v61
	v_add_u32_e32 v62, 1, v62
	s_and_b64 s[2:3], vcc, s[2:3]
	s_and_saveexec_b64 s[4:5], s[2:3]
	global_store_dwordx2 v[58:59], v[66:67], off
	s_or_b64 exec, exec, s[4:5]
	v_add_u32_e32 v60, 1, v60
	v_lshl_add_u64 v[58:59], v[58:59], 0, v[56:57]
	v_cmp_ne_u32_e32 vcc, 0x1100, v60
	s_nop 1
	v_cndmask_b32_e32 v60, 0, v60, vcc
	ds_read2_b64 v[26:29], v63 offset1:32
	v_and_b32_e32 v64, 0xfffffeff, v60
	v_and_b32_e32 v65, 0xffffefff, v60
	v_cmp_eq_u32_e32 vcc, 0, v64
	v_cmp_eq_u32_e64 s[2:3], s33, v65
	v_add_u32_e32 v63, 0x210, v63
	s_nop 0
	v_cndmask_b32_e64 v52, 1.0, 0, vcc
	v_cndmask_b32_e64 v54, 1.0, 0, s[2:3]
	s_waitcnt lgkmcnt(0)
	v_lshlrev_b32_e32 v2, 16, v26
	v_and_b32_e32 v3, 0xffff0000, v26
	v_lshlrev_b32_e32 v4, 16, v27
	v_and_b32_e32 v5, 0xffff0000, v27
	v_lshlrev_b32_e32 v14, 16, v28
	v_and_b32_e32 v15, 0xffff0000, v28
	v_lshlrev_b32_e32 v16, 16, v29
	v_and_b32_e32 v17, 0xffff0000, v29
	v_pk_fma_f32 v[30:31], v[146:147], v[22:23], v[158:159]
	v_pk_fma_f32 v[32:33], v[148:149], v[24:25], v[160:161]
	v_pk_mul_f32 v[38:39], v[52:53], v[18:19] op_sel_hi:[0,1]
	v_pk_mul_f32 v[40:41], v[52:53], v[20:21] op_sel_hi:[0,1]
	v_pk_fma_f32 v[30:31], v[142:143], v[38:39], v[30:31]
	v_pk_fma_f32 v[32:33], v[144:145], v[40:41], v[32:33]
	v_pk_mul_f32 v[38:39], v[54:55], v[14:15] op_sel_hi:[0,1]
	v_pk_mul_f32 v[40:41], v[54:55], v[16:17] op_sel_hi:[0,1]
	v_pk_fma_f32 v[30:31], v[150:151], v[38:39], v[30:31]
	v_pk_fma_f32 v[32:33], v[152:153], v[40:41], v[32:33]
	v_pk_fma_f32 v[34:35], v[134:135], v[10:11], v[154:155]
	v_pk_fma_f32 v[36:37], v[136:137], v[12:13], v[156:157]
	v_pk_mul_f32 v[38:39], v[52:53], v[6:7] op_sel_hi:[0,1]
	v_pk_mul_f32 v[40:41], v[52:53], v[8:9] op_sel_hi:[0,1]
	v_pk_fma_f32 v[34:35], v[130:131], v[38:39], v[34:35]
	v_pk_fma_f32 v[36:37], v[132:133], v[40:41], v[36:37]
	v_pk_mul_f32 v[38:39], v[54:55], v[2:3] op_sel_hi:[0,1]
	v_pk_mul_f32 v[40:41], v[54:55], v[4:5] op_sel_hi:[0,1]
	v_pk_fma_f32 v[34:35], v[138:139], v[38:39], v[34:35]
	v_pk_fma_f32 v[36:37], v[140:141], v[40:41], v[36:37]
	v_mul_f32_e32 v42, 0xbfb8aa3b, v30
	v_exp_f32_e32 v42, v42
	v_mul_f32_e32 v43, 0xbfb8aa3b, v31
	v_exp_f32_e32 v43, v43
	v_mul_f32_e32 v44, 0xbfb8aa3b, v32
	v_exp_f32_e32 v44, v44
	v_mul_f32_e32 v45, 0xbfb8aa3b, v33
	v_exp_f32_e32 v45, v45
	v_pk_add_f32 v[42:43], v[42:43], 1.0 op_sel_hi:[1,0]
	v_pk_add_f32 v[44:45], v[44:45], 1.0 op_sel_hi:[1,0]
	v_rcp_f32_e32 v46, v42
	v_rcp_f32_e32 v47, v43
	v_rcp_f32_e32 v48, v44
	v_rcp_f32_e32 v49, v45
	v_mul_f32_e32 v46, v30, v46
	v_mul_f32_e32 v47, v31, v47
	v_mul_f32_e32 v48, v32, v48
	v_mul_f32_e32 v49, v33, v49
	v_pk_mul_f32 v[34:35], v[34:35], v[46:47]
	v_pk_mul_f32 v[36:37], v[36:37], v[48:49]
	v_cvt_pk_bf16_f32 v66, v34, v35
	v_cvt_pk_bf16_f32 v67, v36, v37
	v_cmp_gt_i32_e32 vcc, s33, v61
	v_cmp_gt_i32_e64 s[2:3], s14, v62
	v_add_u32_e32 v61, 1, v61
	v_add_u32_e32 v62, 1, v62
	s_and_b64 s[2:3], vcc, s[2:3]
	s_and_saveexec_b64 s[4:5], s[2:3]
	global_store_dwordx2 v[58:59], v[66:67], off
	s_or_b64 exec, exec, s[4:5]
	v_add_u32_e32 v60, 1, v60
	v_lshl_add_u64 v[58:59], v[58:59], 0, v[56:57]
	v_cmp_ne_u32_e32 vcc, 0x1100, v60
	s_nop 1
	v_cndmask_b32_e32 v60, 0, v60, vcc
	ds_read2_b64 v[26:29], v63 offset1:32
	v_and_b32_e32 v64, 0xfffffeff, v60
	v_and_b32_e32 v65, 0xffffefff, v60
	v_cmp_eq_u32_e32 vcc, 0, v64
	v_cmp_eq_u32_e64 s[2:3], s33, v65
	v_add_u32_e32 v63, 0x210, v63
	s_nop 0
	v_cndmask_b32_e64 v52, 1.0, 0, vcc
	v_cndmask_b32_e64 v54, 1.0, 0, s[2:3]
	s_waitcnt lgkmcnt(0)
	v_lshlrev_b32_e32 v6, 16, v26
	v_and_b32_e32 v7, 0xffff0000, v26
	v_lshlrev_b32_e32 v8, 16, v27
	v_and_b32_e32 v9, 0xffff0000, v27
	v_lshlrev_b32_e32 v18, 16, v28
	v_and_b32_e32 v19, 0xffff0000, v28
	v_lshlrev_b32_e32 v20, 16, v29
	v_and_b32_e32 v21, 0xffff0000, v29
	v_pk_fma_f32 v[30:31], v[146:147], v[14:15], v[158:159]
	v_pk_fma_f32 v[32:33], v[148:149], v[16:17], v[160:161]
	v_pk_mul_f32 v[38:39], v[52:53], v[22:23] op_sel_hi:[0,1]
	v_pk_mul_f32 v[40:41], v[52:53], v[24:25] op_sel_hi:[0,1]
	v_pk_fma_f32 v[30:31], v[142:143], v[38:39], v[30:31]
	v_pk_fma_f32 v[32:33], v[144:145], v[40:41], v[32:33]
	v_pk_mul_f32 v[38:39], v[54:55], v[18:19] op_sel_hi:[0,1]
	v_pk_mul_f32 v[40:41], v[54:55], v[20:21] op_sel_hi:[0,1]
	v_pk_fma_f32 v[30:31], v[150:151], v[38:39], v[30:31]
	v_pk_fma_f32 v[32:33], v[152:153], v[40:41], v[32:33]
	v_pk_fma_f32 v[34:35], v[134:135], v[2:3], v[154:155]
	v_pk_fma_f32 v[36:37], v[136:137], v[4:5], v[156:157]
	v_pk_mul_f32 v[38:39], v[52:53], v[10:11] op_sel_hi:[0,1]
	v_pk_mul_f32 v[40:41], v[52:53], v[12:13] op_sel_hi:[0,1]
	v_pk_fma_f32 v[34:35], v[130:131], v[38:39], v[34:35]
	v_pk_fma_f32 v[36:37], v[132:133], v[40:41], v[36:37]
	v_pk_mul_f32 v[38:39], v[54:55], v[6:7] op_sel_hi:[0,1]
	v_pk_mul_f32 v[40:41], v[54:55], v[8:9] op_sel_hi:[0,1]
	v_pk_fma_f32 v[34:35], v[138:139], v[38:39], v[34:35]
	v_pk_fma_f32 v[36:37], v[140:141], v[40:41], v[36:37]
	v_mul_f32_e32 v42, 0xbfb8aa3b, v30
	v_exp_f32_e32 v42, v42
	v_mul_f32_e32 v43, 0xbfb8aa3b, v31
	v_exp_f32_e32 v43, v43
	v_mul_f32_e32 v44, 0xbfb8aa3b, v32
	v_exp_f32_e32 v44, v44
	v_mul_f32_e32 v45, 0xbfb8aa3b, v33
	v_exp_f32_e32 v45, v45
	v_pk_add_f32 v[42:43], v[42:43], 1.0 op_sel_hi:[1,0]
	v_pk_add_f32 v[44:45], v[44:45], 1.0 op_sel_hi:[1,0]
	v_rcp_f32_e32 v46, v42
	v_rcp_f32_e32 v47, v43
	v_rcp_f32_e32 v48, v44
	v_rcp_f32_e32 v49, v45
	v_mul_f32_e32 v46, v30, v46
	v_mul_f32_e32 v47, v31, v47
	v_mul_f32_e32 v48, v32, v48
	v_mul_f32_e32 v49, v33, v49
	v_pk_mul_f32 v[34:35], v[34:35], v[46:47]
	v_pk_mul_f32 v[36:37], v[36:37], v[48:49]
	v_cvt_pk_bf16_f32 v66, v34, v35
	v_cvt_pk_bf16_f32 v67, v36, v37
	v_cmp_gt_i32_e32 vcc, s33, v61
	v_cmp_gt_i32_e64 s[2:3], s14, v62
	v_add_u32_e32 v61, 1, v61
	v_add_u32_e32 v62, 1, v62
	s_and_b64 s[2:3], vcc, s[2:3]
	s_and_saveexec_b64 s[4:5], s[2:3]
	global_store_dwordx2 v[58:59], v[66:67], off
	s_or_b64 exec, exec, s[4:5]
	v_add_u32_e32 v60, 1, v60
	v_lshl_add_u64 v[58:59], v[58:59], 0, v[56:57]
	v_cmp_ne_u32_e32 vcc, 0x1100, v60
	s_nop 1
	v_cndmask_b32_e32 v60, 0, v60, vcc
	ds_read2_b64 v[26:29], v63 offset1:32
	v_and_b32_e32 v64, 0xfffffeff, v60
	v_and_b32_e32 v65, 0xffffefff, v60
	v_cmp_eq_u32_e32 vcc, 0, v64
	v_cmp_eq_u32_e64 s[2:3], s33, v65
	v_add_u32_e32 v63, 0x210, v63
	s_nop 0
	v_cndmask_b32_e64 v52, 1.0, 0, vcc
	v_cndmask_b32_e64 v54, 1.0, 0, s[2:3]
	s_waitcnt lgkmcnt(0)
	v_lshlrev_b32_e32 v10, 16, v26
	v_and_b32_e32 v11, 0xffff0000, v26
	v_lshlrev_b32_e32 v12, 16, v27
	v_and_b32_e32 v13, 0xffff0000, v27
	v_lshlrev_b32_e32 v22, 16, v28
	v_and_b32_e32 v23, 0xffff0000, v28
	v_lshlrev_b32_e32 v24, 16, v29
	v_and_b32_e32 v25, 0xffff0000, v29
	v_pk_fma_f32 v[30:31], v[146:147], v[18:19], v[158:159]
	v_pk_fma_f32 v[32:33], v[148:149], v[20:21], v[160:161]
	v_pk_mul_f32 v[38:39], v[52:53], v[14:15] op_sel_hi:[0,1]
	v_pk_mul_f32 v[40:41], v[52:53], v[16:17] op_sel_hi:[0,1]
	v_pk_fma_f32 v[30:31], v[142:143], v[38:39], v[30:31]
	v_pk_fma_f32 v[32:33], v[144:145], v[40:41], v[32:33]
	v_pk_mul_f32 v[38:39], v[54:55], v[22:23] op_sel_hi:[0,1]
	v_pk_mul_f32 v[40:41], v[54:55], v[24:25] op_sel_hi:[0,1]
	v_pk_fma_f32 v[30:31], v[150:151], v[38:39], v[30:31]
	v_pk_fma_f32 v[32:33], v[152:153], v[40:41], v[32:33]
	v_pk_fma_f32 v[34:35], v[134:135], v[6:7], v[154:155]
	v_pk_fma_f32 v[36:37], v[136:137], v[8:9], v[156:157]
	v_pk_mul_f32 v[38:39], v[52:53], v[2:3] op_sel_hi:[0,1]
	v_pk_mul_f32 v[40:41], v[52:53], v[4:5] op_sel_hi:[0,1]
	v_pk_fma_f32 v[34:35], v[130:131], v[38:39], v[34:35]
	v_pk_fma_f32 v[36:37], v[132:133], v[40:41], v[36:37]
	v_pk_mul_f32 v[38:39], v[54:55], v[10:11] op_sel_hi:[0,1]
	v_pk_mul_f32 v[40:41], v[54:55], v[12:13] op_sel_hi:[0,1]
	v_pk_fma_f32 v[34:35], v[138:139], v[38:39], v[34:35]
	v_pk_fma_f32 v[36:37], v[140:141], v[40:41], v[36:37]
	v_mul_f32_e32 v42, 0xbfb8aa3b, v30
	v_exp_f32_e32 v42, v42
	v_mul_f32_e32 v43, 0xbfb8aa3b, v31
	v_exp_f32_e32 v43, v43
	v_mul_f32_e32 v44, 0xbfb8aa3b, v32
	v_exp_f32_e32 v44, v44
	v_mul_f32_e32 v45, 0xbfb8aa3b, v33
	v_exp_f32_e32 v45, v45
	v_pk_add_f32 v[42:43], v[42:43], 1.0 op_sel_hi:[1,0]
	v_pk_add_f32 v[44:45], v[44:45], 1.0 op_sel_hi:[1,0]
	v_rcp_f32_e32 v46, v42
	v_rcp_f32_e32 v47, v43
	v_rcp_f32_e32 v48, v44
	v_rcp_f32_e32 v49, v45
	v_mul_f32_e32 v46, v30, v46
	v_mul_f32_e32 v47, v31, v47
	v_mul_f32_e32 v48, v32, v48
	v_mul_f32_e32 v49, v33, v49
	v_pk_mul_f32 v[34:35], v[34:35], v[46:47]
	v_pk_mul_f32 v[36:37], v[36:37], v[48:49]
	v_cvt_pk_bf16_f32 v66, v34, v35
	v_cvt_pk_bf16_f32 v67, v36, v37
	v_cmp_gt_i32_e32 vcc, s33, v61
	v_cmp_gt_i32_e64 s[2:3], s14, v62
	v_add_u32_e32 v61, 1, v61
	v_add_u32_e32 v62, 1, v62
	s_and_b64 s[2:3], vcc, s[2:3]
	s_and_saveexec_b64 s[4:5], s[2:3]
	global_store_dwordx2 v[58:59], v[66:67], off
	s_or_b64 exec, exec, s[4:5]
	v_add_u32_e32 v60, 1, v60
	v_lshl_add_u64 v[58:59], v[58:59], 0, v[56:57]
	v_cmp_ne_u32_e32 vcc, 0x1100, v60
	s_nop 1
	v_cndmask_b32_e32 v60, 0, v60, vcc
	ds_read2_b64 v[26:29], v63 offset1:32
	v_and_b32_e32 v64, 0xfffffeff, v60
	v_and_b32_e32 v65, 0xffffefff, v60
	v_cmp_eq_u32_e32 vcc, 0, v64
	v_cmp_eq_u32_e64 s[2:3], s33, v65
	v_add_u32_e32 v63, 0x210, v63
	s_nop 0
	v_cndmask_b32_e64 v52, 1.0, 0, vcc
	v_cndmask_b32_e64 v54, 1.0, 0, s[2:3]
	s_waitcnt lgkmcnt(0)
	v_lshlrev_b32_e32 v2, 16, v26
	v_and_b32_e32 v3, 0xffff0000, v26
	v_lshlrev_b32_e32 v4, 16, v27
	v_and_b32_e32 v5, 0xffff0000, v27
	v_lshlrev_b32_e32 v14, 16, v28
	v_and_b32_e32 v15, 0xffff0000, v28
	v_lshlrev_b32_e32 v16, 16, v29
	v_and_b32_e32 v17, 0xffff0000, v29
	v_pk_fma_f32 v[30:31], v[146:147], v[22:23], v[158:159]
	v_pk_fma_f32 v[32:33], v[148:149], v[24:25], v[160:161]
	v_pk_mul_f32 v[38:39], v[52:53], v[18:19] op_sel_hi:[0,1]
	v_pk_mul_f32 v[40:41], v[52:53], v[20:21] op_sel_hi:[0,1]
	v_pk_fma_f32 v[30:31], v[142:143], v[38:39], v[30:31]
	v_pk_fma_f32 v[32:33], v[144:145], v[40:41], v[32:33]
	v_pk_mul_f32 v[38:39], v[54:55], v[14:15] op_sel_hi:[0,1]
	v_pk_mul_f32 v[40:41], v[54:55], v[16:17] op_sel_hi:[0,1]
	v_pk_fma_f32 v[30:31], v[150:151], v[38:39], v[30:31]
	v_pk_fma_f32 v[32:33], v[152:153], v[40:41], v[32:33]
	v_pk_fma_f32 v[34:35], v[134:135], v[10:11], v[154:155]
	v_pk_fma_f32 v[36:37], v[136:137], v[12:13], v[156:157]
	v_pk_mul_f32 v[38:39], v[52:53], v[6:7] op_sel_hi:[0,1]
	v_pk_mul_f32 v[40:41], v[52:53], v[8:9] op_sel_hi:[0,1]
	v_pk_fma_f32 v[34:35], v[130:131], v[38:39], v[34:35]
	v_pk_fma_f32 v[36:37], v[132:133], v[40:41], v[36:37]
	v_pk_mul_f32 v[38:39], v[54:55], v[2:3] op_sel_hi:[0,1]
	v_pk_mul_f32 v[40:41], v[54:55], v[4:5] op_sel_hi:[0,1]
	v_pk_fma_f32 v[34:35], v[138:139], v[38:39], v[34:35]
	v_pk_fma_f32 v[36:37], v[140:141], v[40:41], v[36:37]
	v_mul_f32_e32 v42, 0xbfb8aa3b, v30
	v_exp_f32_e32 v42, v42
	v_mul_f32_e32 v43, 0xbfb8aa3b, v31
	v_exp_f32_e32 v43, v43
	v_mul_f32_e32 v44, 0xbfb8aa3b, v32
	v_exp_f32_e32 v44, v44
	v_mul_f32_e32 v45, 0xbfb8aa3b, v33
	v_exp_f32_e32 v45, v45
	v_pk_add_f32 v[42:43], v[42:43], 1.0 op_sel_hi:[1,0]
	v_pk_add_f32 v[44:45], v[44:45], 1.0 op_sel_hi:[1,0]
	v_rcp_f32_e32 v46, v42
	v_rcp_f32_e32 v47, v43
	v_rcp_f32_e32 v48, v44
	v_rcp_f32_e32 v49, v45
	v_mul_f32_e32 v46, v30, v46
	v_mul_f32_e32 v47, v31, v47
	v_mul_f32_e32 v48, v32, v48
	v_mul_f32_e32 v49, v33, v49
	v_pk_mul_f32 v[34:35], v[34:35], v[46:47]
	v_pk_mul_f32 v[36:37], v[36:37], v[48:49]
	v_cvt_pk_bf16_f32 v66, v34, v35
	v_cvt_pk_bf16_f32 v67, v36, v37
	v_cmp_gt_i32_e32 vcc, s33, v61
	v_cmp_gt_i32_e64 s[2:3], s14, v62
	v_add_u32_e32 v61, 1, v61
	v_add_u32_e32 v62, 1, v62
	s_and_b64 s[2:3], vcc, s[2:3]
	s_and_saveexec_b64 s[4:5], s[2:3]
	global_store_dwordx2 v[58:59], v[66:67], off
	s_or_b64 exec, exec, s[4:5]
	v_add_u32_e32 v60, 1, v60
	v_lshl_add_u64 v[58:59], v[58:59], 0, v[56:57]
	v_cmp_ne_u32_e32 vcc, 0x1100, v60
	s_nop 1
	v_cndmask_b32_e32 v60, 0, v60, vcc
	ds_read2_b64 v[26:29], v63 offset1:32
	v_and_b32_e32 v64, 0xfffffeff, v60
	v_and_b32_e32 v65, 0xffffefff, v60
	v_cmp_eq_u32_e32 vcc, 0, v64
	v_cmp_eq_u32_e64 s[2:3], s33, v65
	v_add_u32_e32 v63, 0x210, v63
	s_nop 0
	v_cndmask_b32_e64 v52, 1.0, 0, vcc
	v_cndmask_b32_e64 v54, 1.0, 0, s[2:3]
	s_waitcnt lgkmcnt(0)
	v_lshlrev_b32_e32 v6, 16, v26
	v_and_b32_e32 v7, 0xffff0000, v26
	v_lshlrev_b32_e32 v8, 16, v27
	v_and_b32_e32 v9, 0xffff0000, v27
	v_lshlrev_b32_e32 v18, 16, v28
	v_and_b32_e32 v19, 0xffff0000, v28
	v_lshlrev_b32_e32 v20, 16, v29
	v_and_b32_e32 v21, 0xffff0000, v29
	v_pk_fma_f32 v[30:31], v[146:147], v[14:15], v[158:159]
	v_pk_fma_f32 v[32:33], v[148:149], v[16:17], v[160:161]
	v_pk_mul_f32 v[38:39], v[52:53], v[22:23] op_sel_hi:[0,1]
	v_pk_mul_f32 v[40:41], v[52:53], v[24:25] op_sel_hi:[0,1]
	v_pk_fma_f32 v[30:31], v[142:143], v[38:39], v[30:31]
	v_pk_fma_f32 v[32:33], v[144:145], v[40:41], v[32:33]
	v_pk_mul_f32 v[38:39], v[54:55], v[18:19] op_sel_hi:[0,1]
	v_pk_mul_f32 v[40:41], v[54:55], v[20:21] op_sel_hi:[0,1]
	v_pk_fma_f32 v[30:31], v[150:151], v[38:39], v[30:31]
	v_pk_fma_f32 v[32:33], v[152:153], v[40:41], v[32:33]
	v_pk_fma_f32 v[34:35], v[134:135], v[2:3], v[154:155]
	v_pk_fma_f32 v[36:37], v[136:137], v[4:5], v[156:157]
	v_pk_mul_f32 v[38:39], v[52:53], v[10:11] op_sel_hi:[0,1]
	v_pk_mul_f32 v[40:41], v[52:53], v[12:13] op_sel_hi:[0,1]
	v_pk_fma_f32 v[34:35], v[130:131], v[38:39], v[34:35]
	v_pk_fma_f32 v[36:37], v[132:133], v[40:41], v[36:37]
	v_pk_mul_f32 v[38:39], v[54:55], v[6:7] op_sel_hi:[0,1]
	v_pk_mul_f32 v[40:41], v[54:55], v[8:9] op_sel_hi:[0,1]
	v_pk_fma_f32 v[34:35], v[138:139], v[38:39], v[34:35]
	v_pk_fma_f32 v[36:37], v[140:141], v[40:41], v[36:37]
	v_mul_f32_e32 v42, 0xbfb8aa3b, v30
	v_exp_f32_e32 v42, v42
	v_mul_f32_e32 v43, 0xbfb8aa3b, v31
	v_exp_f32_e32 v43, v43
	v_mul_f32_e32 v44, 0xbfb8aa3b, v32
	v_exp_f32_e32 v44, v44
	v_mul_f32_e32 v45, 0xbfb8aa3b, v33
	v_exp_f32_e32 v45, v45
	v_pk_add_f32 v[42:43], v[42:43], 1.0 op_sel_hi:[1,0]
	v_pk_add_f32 v[44:45], v[44:45], 1.0 op_sel_hi:[1,0]
	v_rcp_f32_e32 v46, v42
	v_rcp_f32_e32 v47, v43
	v_rcp_f32_e32 v48, v44
	v_rcp_f32_e32 v49, v45
	v_mul_f32_e32 v46, v30, v46
	v_mul_f32_e32 v47, v31, v47
	v_mul_f32_e32 v48, v32, v48
	v_mul_f32_e32 v49, v33, v49
	v_pk_mul_f32 v[34:35], v[34:35], v[46:47]
	v_pk_mul_f32 v[36:37], v[36:37], v[48:49]
	v_cvt_pk_bf16_f32 v66, v34, v35
	v_cvt_pk_bf16_f32 v67, v36, v37
	v_cmp_gt_i32_e32 vcc, s33, v61
	v_cmp_gt_i32_e64 s[2:3], s14, v62
	v_add_u32_e32 v61, 1, v61
	v_add_u32_e32 v62, 1, v62
	s_and_b64 s[2:3], vcc, s[2:3]
	s_and_saveexec_b64 s[4:5], s[2:3]
	global_store_dwordx2 v[58:59], v[66:67], off
	s_or_b64 exec, exec, s[4:5]
	v_add_u32_e32 v60, 1, v60
	v_lshl_add_u64 v[58:59], v[58:59], 0, v[56:57]
	v_cmp_ne_u32_e32 vcc, 0x1100, v60
	s_nop 1
	v_cndmask_b32_e32 v60, 0, v60, vcc
	ds_read2_b64 v[26:29], v63 offset1:32
	v_and_b32_e32 v64, 0xfffffeff, v60
	v_and_b32_e32 v65, 0xffffefff, v60
	v_cmp_eq_u32_e32 vcc, 0, v64
	v_cmp_eq_u32_e64 s[2:3], s33, v65
	v_add_u32_e32 v63, 0x210, v63
	s_nop 0
	v_cndmask_b32_e64 v52, 1.0, 0, vcc
	v_cndmask_b32_e64 v54, 1.0, 0, s[2:3]
	s_waitcnt lgkmcnt(0)
	v_lshlrev_b32_e32 v10, 16, v26
	v_and_b32_e32 v11, 0xffff0000, v26
	v_lshlrev_b32_e32 v12, 16, v27
	v_and_b32_e32 v13, 0xffff0000, v27
	v_lshlrev_b32_e32 v22, 16, v28
	v_and_b32_e32 v23, 0xffff0000, v28
	v_lshlrev_b32_e32 v24, 16, v29
	v_and_b32_e32 v25, 0xffff0000, v29
	v_pk_fma_f32 v[30:31], v[146:147], v[18:19], v[158:159]
	v_pk_fma_f32 v[32:33], v[148:149], v[20:21], v[160:161]
	v_pk_mul_f32 v[38:39], v[52:53], v[14:15] op_sel_hi:[0,1]
	v_pk_mul_f32 v[40:41], v[52:53], v[16:17] op_sel_hi:[0,1]
	v_pk_fma_f32 v[30:31], v[142:143], v[38:39], v[30:31]
	v_pk_fma_f32 v[32:33], v[144:145], v[40:41], v[32:33]
	v_pk_mul_f32 v[38:39], v[54:55], v[22:23] op_sel_hi:[0,1]
	v_pk_mul_f32 v[40:41], v[54:55], v[24:25] op_sel_hi:[0,1]
	v_pk_fma_f32 v[30:31], v[150:151], v[38:39], v[30:31]
	v_pk_fma_f32 v[32:33], v[152:153], v[40:41], v[32:33]
	v_pk_fma_f32 v[34:35], v[134:135], v[6:7], v[154:155]
	v_pk_fma_f32 v[36:37], v[136:137], v[8:9], v[156:157]
	v_pk_mul_f32 v[38:39], v[52:53], v[2:3] op_sel_hi:[0,1]
	v_pk_mul_f32 v[40:41], v[52:53], v[4:5] op_sel_hi:[0,1]
	v_pk_fma_f32 v[34:35], v[130:131], v[38:39], v[34:35]
	v_pk_fma_f32 v[36:37], v[132:133], v[40:41], v[36:37]
	v_pk_mul_f32 v[38:39], v[54:55], v[10:11] op_sel_hi:[0,1]
	v_pk_mul_f32 v[40:41], v[54:55], v[12:13] op_sel_hi:[0,1]
	v_pk_fma_f32 v[34:35], v[138:139], v[38:39], v[34:35]
	v_pk_fma_f32 v[36:37], v[140:141], v[40:41], v[36:37]
	v_mul_f32_e32 v42, 0xbfb8aa3b, v30
	v_exp_f32_e32 v42, v42
	v_mul_f32_e32 v43, 0xbfb8aa3b, v31
	v_exp_f32_e32 v43, v43
	v_mul_f32_e32 v44, 0xbfb8aa3b, v32
	v_exp_f32_e32 v44, v44
	v_mul_f32_e32 v45, 0xbfb8aa3b, v33
	v_exp_f32_e32 v45, v45
	v_pk_add_f32 v[42:43], v[42:43], 1.0 op_sel_hi:[1,0]
	v_pk_add_f32 v[44:45], v[44:45], 1.0 op_sel_hi:[1,0]
	v_rcp_f32_e32 v46, v42
	v_rcp_f32_e32 v47, v43
	v_rcp_f32_e32 v48, v44
	v_rcp_f32_e32 v49, v45
	v_mul_f32_e32 v46, v30, v46
	v_mul_f32_e32 v47, v31, v47
	v_mul_f32_e32 v48, v32, v48
	v_mul_f32_e32 v49, v33, v49
	v_pk_mul_f32 v[34:35], v[34:35], v[46:47]
	v_pk_mul_f32 v[36:37], v[36:37], v[48:49]
	v_cvt_pk_bf16_f32 v66, v34, v35
	v_cvt_pk_bf16_f32 v67, v36, v37
	v_cmp_gt_i32_e32 vcc, s33, v61
	v_cmp_gt_i32_e64 s[2:3], s14, v62
	v_add_u32_e32 v61, 1, v61
	v_add_u32_e32 v62, 1, v62
	s_and_b64 s[2:3], vcc, s[2:3]
	s_and_saveexec_b64 s[4:5], s[2:3]
	global_store_dwordx2 v[58:59], v[66:67], off
	s_or_b64 exec, exec, s[4:5]
	v_add_u32_e32 v60, 1, v60
	v_lshl_add_u64 v[58:59], v[58:59], 0, v[56:57]
	v_cmp_ne_u32_e32 vcc, 0x1100, v60
	s_nop 1
	v_cndmask_b32_e32 v60, 0, v60, vcc
